# attention unit epilogue in one pass: comp-0 waves finish block A while comp-1 waves finish block B through the same compiled combine/row-norm code (comp-1 computes -x with the gain constant negated fo
# speedup vs baseline: 1.0114x; 1.0027x over previous
; #define LAS __attribute__((address_space(3)))
; __device__ __forceinline__ int crow(int r, int hi) { return (r & 3) + 8 * (r >> 2) + 4 * hi; }
; template <int VAR>
; __device__ __forceinline__ void attn_unit(const Args& a, int l, int b, int h, int qrow0  , bool ctxu, const bf16* Z, bf16* Y, LAS unsigned char* lds) {
;     ...
;     float lam, omli;
;     { float s1 = 0.f, s2 = 0.f;
;       for (int i = 0; i < 32; ++i) { s1 += a.lam_q1[l * 32 + i] * a.lam_k1[l * 32 + i]; s2 += a.lam_q2[l * 32 + i] * a.lam_k2[l * 32 + i]; }
;       const float li = 0.8f - 0.6f * expf(-0.3f * (float)l); lam = expf(s1) - expf(s2) + li; omli = 1.f - li; }
;     LAS float* stg = (LAS float*)(lds + AT_ST) + wq * 2048;
;     if (comp == 1) {
; #pragma unroll
;         for (int r = 0; r < 16; ++r) { const int qr = crow(r, hi); const float il = lam * __builtin_amdgcn_rcpf(lacc[r]); stg[qr * 64 + r32] = o0[r] * il; stg[qr * 64 + 32 + r32] = o1[r] * il; }
;     }
;     __syncthreads();
;     if (comp == 0) {
; #pragma unroll
;         for (int r = 0; r < 16; ++r) { const int qr = crow(r, hi); const float il = __builtin_amdgcn_rcpf(lacc[r]); o0[r] = o0[r] * il - stg[qr * 64 + r32]; o1[r] = o1[r] * il - stg[qr * 64 + 32 + r32]; }
;         asm volatile("s_waitcnt lgkmcnt(0)" ::: "memory");
; #pragma unroll
;         for (int r = 0; r < 16; ++r) { const int qr = crow(r, hi); stg[qr * 64 + r32] = o0[r]; stg[qr * 64 + 32 + r32] = o1[r]; }
.Lat_ndF5:
	ds_read_b128 v[48:51], v144 offset:0
	ds_read_b128 v[52:55], v145 offset:0
	ds_read_b128 v[56:59], v144 offset:4096
	ds_read_b128 v[60:63], v145 offset:4096
	v_mfma_f32_32x32x16_bf16 v[80:95], v[162:165], v[192:195], v[80:95]
	v_mfma_f32_32x32x16_bf16 v[200:215], v[162:165], v[196:199], v[200:215]
	s_add_u32 s33, s33, 1
	s_cmp_lt_u32 s33, 22
	s_cbranch_scc1 .Lat_floop
	v_add_f32_e32 v132, v128, v129
	v_mov_b32_e32 v133, v132
	s_nop 1
	v_permlane32_swap_b32_e32 v132, v133
	v_add_f32_e32 v135, v132, v133
	v_add_f32_e32 v132, v130, v131
	v_mov_b32_e32 v133, v132
	s_nop 1
	v_permlane32_swap_b32_e32 v132, v133
	v_add_f32_e32 v130, v132, v133
	s_nop 7
	s_nop 7
	v_add_f32_e32 v132, v135, v130
	v_mov_b32_e32 v133, 0
	v_add_f32_e64 v132, v132, |v0|
	v_add_f32_e64 v133, v133, |v1|
	v_add_f32_e64 v132, v132, |v2|
	v_add_f32_e64 v133, v133, |v3|
	v_add_f32_e64 v132, v132, |v4|
	v_add_f32_e64 v133, v133, |v5|
	v_add_f32_e64 v132, v132, |v6|
	v_add_f32_e64 v133, v133, |v7|
	v_add_f32_e64 v132, v132, |v8|
	v_add_f32_e64 v133, v133, |v9|
	v_add_f32_e64 v132, v132, |v10|
	v_add_f32_e64 v133, v133, |v11|
	v_add_f32_e64 v132, v132, |v12|
	v_add_f32_e64 v133, v133, |v13|
	v_add_f32_e64 v132, v132, |v14|
	v_add_f32_e64 v133, v133, |v15|
	v_add_f32_e64 v132, v132, |v16|
	v_add_f32_e64 v133, v133, |v17|
	v_add_f32_e64 v132, v132, |v18|
	v_add_f32_e64 v133, v133, |v19|
	v_add_f32_e64 v132, v132, |v20|
	v_add_f32_e64 v133, v133, |v21|
	v_add_f32_e64 v132, v132, |v22|
	v_add_f32_e64 v133, v133, |v23|
	v_add_f32_e64 v132, v132, |v24|
	v_add_f32_e64 v133, v133, |v25|
	v_add_f32_e64 v132, v132, |v26|
	v_add_f32_e64 v133, v133, |v27|
	v_add_f32_e64 v132, v132, |v28|
	v_add_f32_e64 v133, v133, |v29|
	v_add_f32_e64 v132, v132, |v30|
	v_add_f32_e64 v133, v133, |v31|
	v_add_f32_e64 v132, v132, |v80|
	v_add_f32_e64 v133, v133, |v81|
	v_add_f32_e64 v132, v132, |v82|
	v_add_f32_e64 v133, v133, |v83|
	v_add_f32_e64 v132, v132, |v84|
	v_add_f32_e64 v133, v133, |v85|
	v_add_f32_e64 v132, v132, |v86|
	v_add_f32_e64 v133, v133, |v87|
	v_add_f32_e64 v132, v132, |v88|
	v_add_f32_e64 v133, v133, |v89|
	v_add_f32_e64 v132, v132, |v90|
	v_add_f32_e64 v133, v133, |v91|
	v_add_f32_e64 v132, v132, |v92|
	v_add_f32_e64 v133, v133, |v93|
	v_add_f32_e64 v132, v132, |v94|
	v_add_f32_e64 v133, v133, |v95|
	v_add_f32_e64 v132, v132, |v200|
	v_add_f32_e64 v133, v133, |v201|
	v_add_f32_e64 v132, v132, |v202|
	v_add_f32_e64 v133, v133, |v203|
	v_add_f32_e64 v132, v132, |v204|
	v_add_f32_e64 v133, v133, |v205|
	v_add_f32_e64 v132, v132, |v206|
	v_add_f32_e64 v133, v133, |v207|
	v_add_f32_e64 v132, v132, |v208|
	v_add_f32_e64 v133, v133, |v209|
	v_add_f32_e64 v132, v132, |v210|
	v_add_f32_e64 v133, v133, |v211|
	v_add_f32_e64 v132, v132, |v212|
	v_add_f32_e64 v133, v133, |v213|
	v_add_f32_e64 v132, v132, |v214|
	v_add_f32_e64 v133, v133, |v215|
	v_add_f32_e32 v132, v132, v133
	v_mov_b32_e32 v133, 0x76800000
	v_cmp_nlt_f32_e32 vcc, v132, v133
	s_cmp_lg_u64 vcc, 0
	s_cselect_b32 s50, 1, 0
	v_mov_b32_e32 v134, 0x19880
	v_mov_b32_e32 v133, s50
	ds_or_b32 v134, v133
	s_waitcnt lgkmcnt(0)
	s_barrier
	ds_read_b32 v133, v134
	s_waitcnt lgkmcnt(0)
	v_readfirstlane_b32 s50, v133
	s_cmp_lg_u32 s50, 0
	s_cbranch_scc1 .Lat_safe_entry
	s_nop 7
	s_waitcnt lgkmcnt(0)
	ds_write_b32 v148, v135
	s_waitcnt lgkmcnt(0)
	ds_read_b128 v[32:35], v147 offset:0
	ds_read_b128 v[36:39], v147 offset:32
	ds_read_b128 v[40:43], v147 offset:64
	ds_read_b128 v[44:47], v147 offset:96
	s_waitcnt lgkmcnt(0)
	ds_write_b32 v148, v130
	s_waitcnt lgkmcnt(0)
	ds_read_b128 v[104:107], v147 offset:0
	ds_read_b128 v[108:111], v147 offset:32
	ds_read_b128 v[112:115], v147 offset:64
	ds_read_b128 v[116:119], v147 offset:96
	s_waitcnt lgkmcnt(0)
	s_mov_b32 s93, 2
	s_waitcnt vmcnt(0)
	v_or_b32_e32 v132, s58, v228
	v_mov_b32_e32 v133, 0
	v_lshl_add_u64 v[132:133], v[132:133], 2, s[78:79]
	global_load_dwordx4 v[100:103], v[132:133], off offset:16
	global_load_dwordx4 v[96:99], v[132:133], off
	s_setprio 0
	s_bfe_u32 s9, s29, 0x20006
	s_lshl_b32 s9, s9, 13
	v_lshlrev_b32_e32 v162, 10, v248
	v_lshlrev_b32_e32 v163, 2, v247
	v_add3_u32 v52, s9, v162, v163
	s_add_i32 s50, s9, 0x11800
	v_add_u32_e32 v164, 0x11800, v52
	s_ashr_i32 s8, s29, 8
	s_cmp_eq_u32 s8, 1
	s_cbranch_scc1 .Lat_e1c1
; __device__ __forceinline__ int crow(int r, int hi) { return (r & 3) + 8 * (r >> 2) + 4 * hi; }
; template <int VAR>
; __device__ __forceinline__ void attn_unit(const Args& a, int l, int b, int h, int qrow0  , bool ctxu, const bf16* Z, bf16* Y, LAS unsigned char* lds) {
;     ...
;     if (comp == 1) {
; #pragma unroll
;         for (int r = 0; r < 16; ++r) { const int qr = crow(r, hi); const float il = lam * __builtin_amdgcn_rcpf(lacc[r]); stg[qr * 64 + r32] = o0[r] * il; stg[qr * 64 + 32 + r32] = o1[r] * il; }
;     }
;     __syncthreads();
;     if (comp == 0) {
; #pragma unroll
;         for (int r = 0; r < 16; ++r) { const int qr = crow(r, hi); const float il = __builtin_amdgcn_rcpf(lacc[r]); o0[r] = o0[r] * il - stg[qr * 64 + r32]; o1[r] = o1[r] * il - stg[qr * 64 + 32 + r32]; }
;         asm volatile("s_waitcnt lgkmcnt(0)" ::: "memory");
; #pragma unroll
;         for (int r = 0; r < 16; ++r) { const int qr = crow(r, hi); stg[qr * 64 + r32] = o0[r]; stg[qr * 64 + 32 + r32] = o1[r]; }
	v_rcp_f32_e32 v68, v32
	v_rcp_f32_e32 v67, v33
	v_rcp_f32_e32 v66, v34
	v_rcp_f32_e32 v65, v35
	v_rcp_f32_e32 v64, v36
	v_rcp_f32_e32 v63, v37
	v_rcp_f32_e32 v62, v38
	v_rcp_f32_e32 v61, v39
	v_rcp_f32_e32 v60, v40
	v_rcp_f32_e32 v59, v41
	v_rcp_f32_e32 v58, v42
	v_rcp_f32_e32 v57, v43
	v_rcp_f32_e32 v56, v44
	v_rcp_f32_e32 v55, v45
	v_rcp_f32_e32 v54, v46
	v_rcp_f32_e32 v53, v47
	v_rcp_f32_e32 v120, v104
	v_rcp_f32_e32 v121, v105
	v_rcp_f32_e32 v122, v106
	v_rcp_f32_e32 v123, v107
	v_rcp_f32_e32 v124, v108
	v_rcp_f32_e32 v125, v109
	v_rcp_f32_e32 v126, v110
	v_rcp_f32_e32 v127, v111
	v_rcp_f32_e32 v128, v112
	v_rcp_f32_e32 v129, v113
	v_rcp_f32_e32 v130, v114
	v_rcp_f32_e32 v131, v115
	v_rcp_f32_e32 v132, v116
	v_rcp_f32_e32 v133, v117
	v_rcp_f32_e32 v134, v118
	v_rcp_f32_e32 v135, v119
	v_mov_b32_e32 v165, v52
	v_mul_f32_e32 v162, v80, v120
	v_mul_f32_e32 v163, v200, v120
	ds_write2_b32 v165, v162, v163 offset1:32
	v_mul_f32_e32 v162, v81, v121
	v_mul_f32_e32 v163, v201, v121
	ds_write2_b32 v165, v162, v163 offset0:64 offset1:96
	v_mul_f32_e32 v162, v82, v122
	v_mul_f32_e32 v163, v202, v122
	ds_write2_b32 v165, v162, v163 offset0:128 offset1:160
	v_mul_f32_e32 v162, v83, v123
	v_mul_f32_e32 v163, v203, v123
	ds_write2_b32 v165, v162, v163 offset0:192 offset1:224
	v_add_u32_e32 v165, 0x800, v52
	v_mul_f32_e32 v162, v84, v124
	v_mul_f32_e32 v163, v204, v124
	ds_write2_b32 v165, v162, v163 offset1:32
	v_mul_f32_e32 v162, v85, v125
	v_mul_f32_e32 v163, v205, v125
	ds_write2_b32 v165, v162, v163 offset0:64 offset1:96
	v_mul_f32_e32 v162, v86, v126
	v_mul_f32_e32 v163, v206, v126
	ds_write2_b32 v165, v162, v163 offset0:128 offset1:160
	v_mul_f32_e32 v162, v87, v127
	v_mul_f32_e32 v163, v207, v127
	ds_write2_b32 v165, v162, v163 offset0:192 offset1:224
	v_add_u32_e32 v165, 0x1000, v52
	v_mul_f32_e32 v162, v88, v128
	v_mul_f32_e32 v163, v208, v128
	ds_write2_b32 v165, v162, v163 offset1:32
	v_mul_f32_e32 v162, v89, v129
	v_mul_f32_e32 v163, v209, v129
	ds_write2_b32 v165, v162, v163 offset0:64 offset1:96
	v_mul_f32_e32 v162, v90, v130
	v_mul_f32_e32 v163, v210, v130
	ds_write2_b32 v165, v162, v163 offset0:128 offset1:160
	v_mul_f32_e32 v162, v91, v131
	v_mul_f32_e32 v163, v211, v131
	ds_write2_b32 v165, v162, v163 offset0:192 offset1:224
	v_add_u32_e32 v165, 0x1800, v52
	v_mul_f32_e32 v162, v92, v132
	v_mul_f32_e32 v163, v212, v132
	ds_write2_b32 v165, v162, v163 offset1:32
	v_mul_f32_e32 v162, v93, v133
	v_mul_f32_e32 v163, v213, v133
	ds_write2_b32 v165, v162, v163 offset0:64 offset1:96
	v_mul_f32_e32 v162, v94, v134
	v_mul_f32_e32 v163, v214, v134
	ds_write2_b32 v165, v162, v163 offset0:128 offset1:160
	v_mul_f32_e32 v162, v95, v135
	v_mul_f32_e32 v163, v215, v135
	ds_write2_b32 v165, v162, v163 offset0:192 offset1:224
	v_mov_b32_e32 v52, v164
	s_mov_b32 s9, s50
	s_branch .Lat_e1join
; __device__ __forceinline__ int crow(int r, int hi) { return (r & 3) + 8 * (r >> 2) + 4 * hi; }
; template <int VAR>
; __device__ __forceinline__ void attn_unit(const Args& a, int l, int b, int h, int qrow0  , bool ctxu, const bf16* Z, bf16* Y, LAS unsigned char* lds) {
;     ...
;     if (comp == 1) {
; #pragma unroll
;         for (int r = 0; r < 16; ++r) { const int qr = crow(r, hi); const float il = lam * __builtin_amdgcn_rcpf(lacc[r]); stg[qr * 64 + r32] = o0[r] * il; stg[qr * 64 + 32 + r32] = o1[r] * il; }
;     }
;     __syncthreads();
;     if (comp == 0) {
; #pragma unroll
;         for (int r = 0; r < 16; ++r) { const int qr = crow(r, hi); const float il = __builtin_amdgcn_rcpf(lacc[r]); o0[r] = o0[r] * il - stg[qr * 64 + r32]; o1[r] = o1[r] * il - stg[qr * 64 + 32 + r32]; }
;         asm volatile("s_waitcnt lgkmcnt(0)" ::: "memory");
; #pragma unroll
;         for (int r = 0; r < 16; ++r) { const int qr = crow(r, hi); stg[qr * 64 + r32] = o0[r]; stg[qr * 64 + 32 + r32] = o1[r]; }
.Lat_e1c1:
	v_rcp_f32_e32 v120, v32
	v_rcp_f32_e32 v121, v33
	v_rcp_f32_e32 v122, v34
	v_rcp_f32_e32 v123, v35
	v_rcp_f32_e32 v124, v36
	v_rcp_f32_e32 v125, v37
	v_rcp_f32_e32 v126, v38
	v_rcp_f32_e32 v127, v39
	v_rcp_f32_e32 v128, v40
	v_rcp_f32_e32 v129, v41
	v_rcp_f32_e32 v130, v42
	v_rcp_f32_e32 v131, v43
	v_rcp_f32_e32 v132, v44
	v_rcp_f32_e32 v133, v45
	v_rcp_f32_e32 v134, v46
	v_rcp_f32_e32 v135, v47
	v_rcp_f32_e32 v68, v104
	v_rcp_f32_e32 v67, v105
	v_rcp_f32_e32 v66, v106
	v_rcp_f32_e32 v65, v107
	v_rcp_f32_e32 v64, v108
	v_rcp_f32_e32 v63, v109
	v_rcp_f32_e32 v62, v110
	v_rcp_f32_e32 v61, v111
	v_rcp_f32_e32 v60, v112
	v_rcp_f32_e32 v59, v113
	v_rcp_f32_e32 v58, v114
	v_rcp_f32_e32 v57, v115
	v_rcp_f32_e32 v56, v116
	v_rcp_f32_e32 v55, v117
	v_rcp_f32_e32 v54, v118
	v_rcp_f32_e32 v53, v119
	v_mul_f32_e32 v120, v120, v167
	v_mul_f32_e32 v121, v121, v167
	v_mul_f32_e32 v122, v122, v167
	v_mul_f32_e32 v123, v123, v167
	v_mul_f32_e32 v124, v124, v167
	v_mul_f32_e32 v125, v125, v167
	v_mul_f32_e32 v126, v126, v167
	v_mul_f32_e32 v127, v127, v167
	v_mul_f32_e32 v128, v128, v167
	v_mul_f32_e32 v129, v129, v167
	v_mul_f32_e32 v130, v130, v167
	v_mul_f32_e32 v131, v131, v167
	v_mul_f32_e32 v132, v132, v167
	v_mul_f32_e32 v133, v133, v167
	v_mul_f32_e32 v134, v134, v167
	v_mul_f32_e32 v135, v135, v167
	v_mul_f32_e32 v68, v68, v167
	v_mul_f32_e32 v67, v67, v167
	v_mul_f32_e32 v66, v66, v167
	v_mul_f32_e32 v65, v65, v167
	v_mul_f32_e32 v64, v64, v167
	v_mul_f32_e32 v63, v63, v167
	v_mul_f32_e32 v62, v62, v167
	v_mul_f32_e32 v61, v61, v167
	v_mul_f32_e32 v60, v60, v167
	v_mul_f32_e32 v59, v59, v167
	v_mul_f32_e32 v58, v58, v167
	v_mul_f32_e32 v57, v57, v167
	v_mul_f32_e32 v56, v56, v167
	v_mul_f32_e32 v55, v55, v167
	v_mul_f32_e32 v54, v54, v167
	v_mul_f32_e32 v53, v53, v167
	v_mov_b32_e32 v165, v164
	v_mul_f32_e32 v162, v0, v120
	v_mul_f32_e32 v163, v16, v120
	ds_write2_b32 v165, v162, v163 offset1:32
	v_mul_f32_e32 v162, v1, v121
	v_mul_f32_e32 v163, v17, v121
	ds_write2_b32 v165, v162, v163 offset0:64 offset1:96
	v_mul_f32_e32 v162, v2, v122
	v_mul_f32_e32 v163, v18, v122
	ds_write2_b32 v165, v162, v163 offset0:128 offset1:160
	v_mul_f32_e32 v162, v3, v123
	v_mul_f32_e32 v163, v19, v123
	ds_write2_b32 v165, v162, v163 offset0:192 offset1:224
	v_add_u32_e32 v165, 0x800, v164
	v_mul_f32_e32 v162, v4, v124
	v_mul_f32_e32 v163, v20, v124
	ds_write2_b32 v165, v162, v163 offset1:32
	v_mul_f32_e32 v162, v5, v125
	v_mul_f32_e32 v163, v21, v125
	ds_write2_b32 v165, v162, v163 offset0:64 offset1:96
	v_mul_f32_e32 v162, v6, v126
	v_mul_f32_e32 v163, v22, v126
	ds_write2_b32 v165, v162, v163 offset0:128 offset1:160
	v_mul_f32_e32 v162, v7, v127
	v_mul_f32_e32 v163, v23, v127
	ds_write2_b32 v165, v162, v163 offset0:192 offset1:224
	v_add_u32_e32 v165, 0x1000, v164
	v_mul_f32_e32 v162, v8, v128
	v_mul_f32_e32 v163, v24, v128
	ds_write2_b32 v165, v162, v163 offset1:32
	v_mul_f32_e32 v162, v9, v129
	v_mul_f32_e32 v163, v25, v129
	ds_write2_b32 v165, v162, v163 offset0:64 offset1:96
	v_mul_f32_e32 v162, v10, v130
	v_mul_f32_e32 v163, v26, v130
	ds_write2_b32 v165, v162, v163 offset0:128 offset1:160
	v_mul_f32_e32 v162, v11, v131
	v_mul_f32_e32 v163, v27, v131
	ds_write2_b32 v165, v162, v163 offset0:192 offset1:224
	v_add_u32_e32 v165, 0x1800, v164
	v_mul_f32_e32 v162, v12, v132
	v_mul_f32_e32 v163, v28, v132
	ds_write2_b32 v165, v162, v163 offset1:32
	v_mul_f32_e32 v162, v13, v133
	v_mul_f32_e32 v163, v29, v133
	ds_write2_b32 v165, v162, v163 offset0:64 offset1:96
	v_mul_f32_e32 v162, v14, v134
	v_mul_f32_e32 v163, v30, v134
	ds_write2_b32 v165, v162, v163 offset0:128 offset1:160
	v_mul_f32_e32 v162, v15, v135
	v_mul_f32_e32 v163, v31, v135
	ds_write2_b32 v165, v162, v163 offset0:192 offset1:224
	v_mov_b32_e32 v0, v80
	v_mov_b32_e32 v16, v200
	v_mov_b32_e32 v1, v81
	v_mov_b32_e32 v17, v201
	v_mov_b32_e32 v2, v82
	v_mov_b32_e32 v18, v202
	v_mov_b32_e32 v3, v83
	v_mov_b32_e32 v19, v203
	v_mov_b32_e32 v4, v84
	v_mov_b32_e32 v20, v204
	v_mov_b32_e32 v5, v85
	v_mov_b32_e32 v21, v205
	v_mov_b32_e32 v6, v86
	v_mov_b32_e32 v22, v206
	v_mov_b32_e32 v7, v87
	v_mov_b32_e32 v23, v207
	v_mov_b32_e32 v8, v88
	v_mov_b32_e32 v24, v208
	v_mov_b32_e32 v9, v89
	v_mov_b32_e32 v25, v209
	v_mov_b32_e32 v10, v90
	v_mov_b32_e32 v26, v210
	v_mov_b32_e32 v11, v91
	v_mov_b32_e32 v27, v211
	v_mov_b32_e32 v12, v92
	v_mov_b32_e32 v28, v212
	v_mov_b32_e32 v13, v93
	v_mov_b32_e32 v29, v213
	v_mov_b32_e32 v14, v94
	v_mov_b32_e32 v30, v214
	v_mov_b32_e32 v15, v95
	v_mov_b32_e32 v31, v215
	s_or_b32 s60, s60, 0x1000
	v_xor_b32_e32 v226, 0x80000000, v226
.Lat_e1join:
	s_waitcnt lgkmcnt(0)
	s_barrier
	s_branch .Lat_ep462

; __global__ void __launch_bounds__(512, 2) fwd_megakernel(Args a) {
;     ...
;                 for (int i = 0;; ++i) { const int j = xm ? cu + i * per : blk + i * G; if (j >= (xm ? 128 : 1024)) break;
;                     const int bh = xm ? xcd * 2 + (j >> 6) : (j >> 6), qb = j & 63; if (rep_ == 0) attn_unit<0>(a, l, bh >> 2, bh & 3, (bh >> 2) * SEQ + qb * 128, false, Zb, Yb, lds); else attn_unit<PROBE_VAR>(a, l, bh >> 2, bh & 3, (bh >> 2) * SEQ + qb * 128, false, Zb, (bf16*)(ws + 384 * MiB), lds); }
.Lat_afterA:
	s_cmp_eq_u32 s93, 2
	s_cbranch_scc0 .Lat_after2p
	s_ashr_i32 s8, s29, 8
	s_cmp_eq_u32 s8, 1
	s_cbranch_scc0 .Lat_done1
	v_xor_b32_e32 v226, 0x80000000, v226
.Lat_done1:
	s_add_i32 s59, s59, 1
	s_branch .LBB0_428

; #define LAS __attribute__((address_space(3)))
; __device__ __forceinline__ float sum8(float v) { v += dppmov<0xB1>(v); v += dppmov<0x4E>(v); v += dppmov<0x141>(v); return v; }
; __device__ __forceinline__ u32x4 pk8(const float (&v)[8]) { u32x4 w; w.x = pk2(v[0], v[1]); w.y = pk2(v[2], v[3]); w.z = pk2(v[4], v[5]); w.w = pk2(v[6], v[7]); return w; }
; __device__ __forceinline__ int crow(int r, int hi) { return (r & 3) + 8 * (r >> 2) + 4 * hi; }
; template <int VAR>
; __device__ __forceinline__ void attn_unit(const Args& a, int l, int b, int h, int qrow0  , bool ctxu, const bf16* Z, bf16* Y, LAS unsigned char* lds) {
;     ...
;     if (comp == 0) {
; #pragma unroll
;         for (int r = 0; r < 16; ++r) { const int qr = crow(r, hi); const float il = __builtin_amdgcn_rcpf(lacc[r]); o0[r] = o0[r] * il - stg[qr * 64 + r32]; o1[r] = o1[r] * il - stg[qr * 64 + 32 + r32]; }
;         asm volatile("s_waitcnt lgkmcnt(0)" ::: "memory");
; #pragma unroll
;         for (int r = 0; r < 16; ++r) { const int qr = crow(r, hi); stg[qr * 64 + r32] = o0[r]; stg[qr * 64 + 32 + r32] = o1[r]; }
;         asm volatile("s_waitcnt lgkmcnt(0)" ::: "memory");
;         const int ch = lane & 7;
;         float gsub[8];
; #pragma unroll
;         for (int i = 0; i < 8; ++i) gsub[i] = a.subln_g[l * 64 + ch * 8 + i] * omli;
; #pragma unroll
;         for (int i = 0; i < 4; ++i) { const int row = i * 8 + (lane >> 3);
;             const f32x4 x0 = *(const LAS f32x4*)(stg + row * 64 + ch * 8), x1 = *(const LAS f32x4*)(stg + row * 64 + ch * 8 + 4);
;             float ss = (x0.x * x0.x + x0.y * x0.y) + (x0.z * x0.z + x0.w * x0.w) + (x1.x * x1.x + x1.y * x1.y) + (x1.z * x1.z + x1.w * x1.w);
;             ss = sum8(ss);
;             const float rs = rsqrtf(ss * (1.f / 64.f) + 1e-6f);
;             float o[8] = {x0.x * rs * gsub[0], x0.y * rs * gsub[1], x0.z * rs * gsub[2], x0.w * rs * gsub[3], x1.x * rs * gsub[4], x1.y * rs * gsub[5], x1.z * rs * gsub[6], x1.w * rs * gsub[7]};
;             *(u32x4*)(Y + (size_t)(qrow0 + wq * 32 + row) * DM + 256 + h * 64 + ch * 8) = pk8(o); }
.Lat_ep462:
	v_add_u32_e32 v33, 0x800, v52
	v_add_u32_e32 v35, 0x1000, v52
	v_add_u32_e32 v36, 0x1800, v52
	ds_read2_b32 v[168:169], v52 offset1:32
	ds_read2_b32 v[170:171], v52 offset0:64 offset1:96
	ds_read2_b32 v[172:173], v52 offset0:128 offset1:160
	ds_read2_b32 v[174:175], v52 offset0:192 offset1:224
	ds_read2_b32 v[176:177], v33 offset1:32
	ds_read2_b32 v[178:179], v33 offset0:64 offset1:96
	ds_read2_b32 v[180:181], v33 offset0:128 offset1:160
	ds_read2_b32 v[182:183], v33 offset0:192 offset1:224
	ds_read2_b32 v[184:185], v35 offset1:32
	ds_read2_b32 v[186:187], v35 offset0:64 offset1:96
	ds_read2_b32 v[188:189], v35 offset0:128 offset1:160
	ds_read2_b32 v[190:191], v35 offset0:192 offset1:224
	v_readlane_b32 s76, v252, 43
	v_or_b32_e32 v216, s58, v228
	v_readlane_b32 s78, v252, 45
	v_readlane_b32 s79, v252, 46
	s_lshl_b32 s72, s28, 1
	v_readlane_b32 s77, v252, 44
	v_readlane_b32 s80, v252, 47
	v_readlane_b32 s81, v252, 48
	v_readlane_b32 s82, v252, 49
	v_readlane_b32 s83, v252, 50
	v_readlane_b32 s84, v252, 51
	v_readlane_b32 s85, v252, 52
	v_readlane_b32 s86, v252, 53
	v_readlane_b32 s87, v252, 54
	v_readlane_b32 s88, v252, 55
	v_readlane_b32 s89, v252, 56
	v_readlane_b32 s90, v252, 57
	v_readlane_b32 s91, v252, 58
	s_waitcnt lgkmcnt(8)
	v_fma_f32 v34, v0, v68, -v168
	v_fma_f32 v16, v16, v68, -v169
	v_fma_f32 v32, v1, v67, -v170
	v_fma_f32 v17, v17, v67, -v171
	v_fma_f32 v2, v2, v66, -v172
	v_fma_f32 v18, v18, v66, -v173
	v_fma_f32 v3, v3, v65, -v174
	v_fma_f32 v19, v19, v65, -v175
	ds_read2_b32 v[192:193], v36 offset1:32
	ds_read2_b32 v[194:195], v36 offset0:64 offset1:96
	ds_read2_b32 v[196:197], v36 offset0:128 offset1:160
	ds_read2_b32 v[198:199], v36 offset0:192 offset1:224
	s_waitcnt lgkmcnt(8)
	v_fma_f32 v4, v4, v64, -v176
	v_fma_f32 v20, v20, v64, -v177
	v_fma_f32 v5, v5, v63, -v178
	v_fma_f32 v21, v21, v63, -v179
	v_fma_f32 v6, v6, v62, -v180
	v_fma_f32 v22, v22, v62, -v181
	v_fma_f32 v7, v7, v61, -v182
	v_fma_f32 v23, v23, v61, -v183
	s_waitcnt lgkmcnt(4)
	v_fma_f32 v8, v8, v60, -v184
	v_fma_f32 v24, v24, v60, -v185
	v_fma_f32 v9, v9, v59, -v186
	v_fma_f32 v25, v25, v59, -v187
	v_fma_f32 v10, v10, v58, -v188
	v_fma_f32 v26, v26, v58, -v189
	v_fma_f32 v11, v11, v57, -v190
	v_fma_f32 v27, v27, v57, -v191
	s_waitcnt lgkmcnt(0)
	v_fma_f32 v12, v12, v56, -v192
	v_fma_f32 v28, v28, v56, -v193
	v_fma_f32 v13, v13, v55, -v194
	v_fma_f32 v29, v29, v55, -v195
	v_fma_f32 v14, v14, v54, -v196
	v_fma_f32 v30, v30, v54, -v197
	v_fma_f32 v0, v15, v53, -v198
	v_fma_f32 v1, v31, v53, -v199
	ds_write2_b32 v52, v34, v16 offset1:32
	ds_write2_b32 v52, v32, v17 offset0:64 offset1:96
	ds_write2_b32 v52, v2, v18 offset0:128 offset1:160
	ds_write2_b32 v52, v3, v19 offset0:192 offset1:224
	ds_write2_b32 v33, v4, v20 offset1:32
	ds_write2_b32 v33, v5, v21 offset0:64 offset1:96
	ds_write2_b32 v33, v6, v22 offset0:128 offset1:160
	ds_write2_b32 v33, v7, v23 offset0:192 offset1:224
	ds_write2_b32 v35, v8, v24 offset1:32
	ds_write2_b32 v35, v9, v25 offset0:64 offset1:96
	ds_write2_b32 v35, v10, v26 offset0:128 offset1:160
	ds_write2_b32 v35, v11, v27 offset0:192 offset1:224
	ds_write2_b32 v36, v12, v28 offset1:32
	ds_write2_b32 v36, v13, v29 offset0:64 offset1:96
	ds_write2_b32 v36, v14, v30 offset0:128 offset1:160
	ds_write2_b32 v36, v0, v1 offset0:192 offset1:224
	s_waitcnt lgkmcnt(0)
	v_lshrrev_b32_e32 v32, 3, v227
	v_lshl_add_u32 v33, v228, 2, s9
	v_lshl_add_u32 v0, v32, 8, v33
	ds_read_b128 v[8:11], v0
	ds_read_b128 v[16:19], v0 offset:16
	v_lshlrev_b32_e32 v216, 1, v228
	s_waitcnt lgkmcnt(1)
	v_pk_mul_f32 v[0:1], v[10:11], v[10:11]
	v_pk_mul_f32 v[2:3], v[8:9], v[8:9]
	v_mov_b32_e32 v227, v8
	v_pk_mov_b32 v[20:21], v[2:3], v[0:1] op_sel:[1,0]
	v_mov_b32_e32 v3, v1
	v_pk_add_f32 v[0:1], v[20:21], v[2:3]
	s_waitcnt lgkmcnt(0)
	v_pk_mul_f32 v[2:3], v[18:19], v[18:19]
	v_pk_mul_f32 v[20:21], v[16:17], v[16:17]
	v_mov_b32_e32 v22, v2
	v_mov_b32_e32 v23, v20
	v_mov_b32_e32 v20, v3
	v_pk_add_f32 v[2:3], v[22:23], v[20:21]
	v_add_f32_e32 v0, v0, v1
	v_add_f32_e32 v0, v0, v3
	v_add_f32_e32 v0, v2, v0
	s_waitcnt vmcnt(0)
	v_mov_b32_e32 v20, v96
	v_add_f32_dpp v0, v0, v0 quad_perm:[1,0,3,2] row_mask:0xf bank_mask:0xf bound_ctrl:1
	s_nop 1
	v_add_f32_dpp v0, v0, v0 quad_perm:[2,3,0,1] row_mask:0xf bank_mask:0xf bound_ctrl:1
	s_nop 1
	v_add_f32_dpp v0, v0, v0 row_half_mirror row_mask:0xf bank_mask:0xf bound_ctrl:1
	v_fmamk_f32 v0, v0, 0x3c800000, v218
	v_cmp_gt_f32_e32 vcc, s66, v0
	v_mul_f32_e32 v1, 0x4b800000, v0
	s_nop 0
	v_cndmask_b32_e32 v0, v0, v1, vcc
	v_rsq_f32_e32 v0, v0
	s_nop 0
	v_mul_f32_e32 v1, 0x45800000, v0
	v_cndmask_b32_e32 v21, v0, v1, vcc
	v_pk_mul_f32 v[0:1], v[226:227], v[20:21]
	v_mov_b32_e32 v227, v9
	v_mov_b32_e32 v20, v97
	v_pk_mul_f32 v[2:3], v[226:227], v[20:21]
	v_mov_b32_e32 v227, v10
	v_mov_b32_e32 v20, v98
	v_pk_mul_f32 v[4:5], v[226:227], v[20:21]
	v_mov_b32_e32 v227, v11
	v_mov_b32_e32 v20, v99
	v_pk_mul_f32 v[6:7], v[226:227], v[20:21]
	v_mov_b32_e32 v227, v16
	v_mov_b32_e32 v20, v100
	v_pk_mul_f32 v[8:9], v[226:227], v[20:21]
	v_mov_b32_e32 v227, v17
	v_mov_b32_e32 v20, v101
	v_pk_mul_f32 v[10:11], v[226:227], v[20:21]
	v_mov_b32_e32 v227, v18
	v_mov_b32_e32 v20, v102
	v_pk_mul_f32 v[12:13], v[226:227], v[20:21]
	v_mov_b32_e32 v227, v19
	v_mov_b32_e32 v20, v103
	v_pk_mul_f32 v[14:15], v[226:227], v[20:21]
	v_or_b32_e32 v20, s60, v32
	v_ashrrev_i32_e32 v21, 31, v20
	v_lshlrev_b64 v[20:21], 11, v[20:21]
	v_lshl_add_u64 v[20:21], s[20:21], 0, v[20:21]
	v_mul_f32_e32 v1, v0, v1
	v_lshl_add_u64 v[20:21], v[20:21], 0, s[72:73]
	v_mul_f32_e32 v3, v2, v3
	v_cvt_pk_bf16_f32 v16, v1, v3
	v_lshl_add_u64 v[20:21], v[20:21], 0, v[216:217]
	v_or_b32_e32 v1, 8, v32
	v_mul_f32_e32 v5, v4, v5
	v_mul_f32_e32 v7, v6, v7
	v_mul_f32_e32 v9, v8, v9
	v_mul_f32_e32 v11, v10, v11
	v_mul_f32_e32 v13, v12, v13
	v_mul_f32_e32 v15, v14, v15
	v_cvt_pk_bf16_f32 v17, v5, v7
	v_cvt_pk_bf16_f32 v18, v9, v11
	v_cvt_pk_bf16_f32 v19, v13, v15
	global_store_dwordx4 v[20:21], v[16:19], off offset:512
	v_lshl_add_u32 v3, v1, 8, v33
	ds_read_b128 v[16:19], v3
	ds_read_b128 v[20:23], v3 offset:16
	s_waitcnt lgkmcnt(1)
; #define LAS __attribute__((address_space(3)))
; __device__ __forceinline__ float sum8(float v) { v += dppmov<0xB1>(v); v += dppmov<0x4E>(v); v += dppmov<0x141>(v); return v; }
; __device__ __forceinline__ u32x4 pk8(const float (&v)[8]) { u32x4 w; w.x = pk2(v[0], v[1]); w.y = pk2(v[2], v[3]); w.z = pk2(v[4], v[5]); w.w = pk2(v[6], v[7]); return w; }
; template <int VAR>
; __device__ __forceinline__ void attn_unit(const Args& a, int l, int b, int h, int qrow0  , bool ctxu, const bf16* Z, bf16* Y, LAS unsigned char* lds) {
;     ...
;         for (int i = 0; i < 4; ++i) { const int row = i * 8 + (lane >> 3);
;             const f32x4 x0 = *(const LAS f32x4*)(stg + row * 64 + ch * 8), x1 = *(const LAS f32x4*)(stg + row * 64 + ch * 8 + 4);
;             float ss = (x0.x * x0.x + x0.y * x0.y) + (x0.z * x0.z + x0.w * x0.w) + (x1.x * x1.x + x1.y * x1.y) + (x1.z * x1.z + x1.w * x1.w);
;             ss = sum8(ss);
;             const float rs = rsqrtf(ss * (1.f / 64.f) + 1e-6f);
;             float o[8] = {x0.x * rs * gsub[0], x0.y * rs * gsub[1], x0.z * rs * gsub[2], x0.w * rs * gsub[3], x1.x * rs * gsub[4], x1.y * rs * gsub[5], x1.z * rs * gsub[6], x1.w * rs * gsub[7]};
;             *(u32x4*)(Y + (size_t)(qrow0 + wq * 32 + row) * DM + 256 + h * 64 + ch * 8) = pk8(o); }
	v_pk_mul_f32 v[24:25], v[18:19], v[18:19]
	v_pk_mul_f32 v[26:27], v[16:17], v[16:17]
	s_nop 0
	v_pk_mov_b32 v[28:29], v[26:27], v[24:25] op_sel:[1,0]
	v_mov_b32_e32 v27, v25
	v_pk_add_f32 v[24:25], v[28:29], v[26:27]
	s_waitcnt lgkmcnt(0)
	v_pk_mul_f32 v[26:27], v[22:23], v[22:23]
	v_pk_mul_f32 v[28:29], v[20:21], v[20:21]
	v_mov_b32_e32 v30, v26
	v_mov_b32_e32 v31, v28
	v_mov_b32_e32 v28, v27
	v_pk_add_f32 v[26:27], v[30:31], v[28:29]
	v_add_f32_e32 v3, v24, v25
	v_add_f32_e32 v3, v3, v27
	v_add_f32_e32 v3, v26, v3
	s_nop 1
	v_add_f32_dpp v3, v3, v3 quad_perm:[1,0,3,2] row_mask:0xf bank_mask:0xf bound_ctrl:1
	s_nop 1
	v_add_f32_dpp v3, v3, v3 quad_perm:[2,3,0,1] row_mask:0xf bank_mask:0xf bound_ctrl:1
	s_nop 1
	v_add_f32_dpp v3, v3, v3 row_half_mirror row_mask:0xf bank_mask:0xf bound_ctrl:1
	v_fmamk_f32 v3, v3, 0x3c800000, v218
	v_cmp_gt_f32_e32 vcc, s66, v3
	v_mul_f32_e32 v5, 0x4b800000, v3
	s_nop 0
	v_cndmask_b32_e32 v3, v3, v5, vcc
	v_rsq_f32_e32 v3, v3
	s_nop 0
	v_mul_f32_e32 v5, 0x45800000, v3
	v_cndmask_b32_e32 v3, v3, v5, vcc
	v_mul_f32_e32 v13, v20, v3
	v_or_b32_e32 v20, s60, v1
	v_mul_f32_e32 v15, v21, v3
	v_ashrrev_i32_e32 v21, 31, v20
	v_lshlrev_b64 v[20:21], 11, v[20:21]
	v_lshl_add_u64 v[20:21], s[20:21], 0, v[20:21]
	v_mul_f32_e32 v5, v16, v3
	v_mul_f32_e32 v7, v17, v3
	v_mul_f32_e32 v9, v18, v3
	v_mul_f32_e32 v11, v19, v3
	v_mul_f32_e32 v16, v22, v3
	v_mul_f32_e32 v3, v23, v3
	v_lshl_add_u64 v[20:21], v[20:21], 0, s[72:73]
	v_mul_f32_e32 v19, v12, v16
	v_mul_f32_e32 v3, v14, v3
	v_lshl_add_u64 v[20:21], v[20:21], 0, v[216:217]
	v_or_b32_e32 v1, 16, v32
	v_mul_f32_e32 v5, v0, v5
	v_mul_f32_e32 v7, v2, v7
	v_mul_f32_e32 v9, v4, v9
	v_mul_f32_e32 v11, v6, v11
	v_mul_f32_e32 v13, v8, v13
	v_mul_f32_e32 v15, v10, v15
	v_cvt_pk_bf16_f32 v16, v5, v7
	v_cvt_pk_bf16_f32 v17, v9, v11
	v_cvt_pk_bf16_f32 v18, v13, v15
	v_cvt_pk_bf16_f32 v19, v19, v3
	global_store_dwordx4 v[20:21], v[16:19], off offset:512
	v_lshl_add_u32 v3, v1, 8, v33
	ds_read_b128 v[16:19], v3
	ds_read_b128 v[20:23], v3 offset:16
	s_waitcnt lgkmcnt(1)
	v_pk_mul_f32 v[24:25], v[18:19], v[18:19]
	v_pk_mul_f32 v[26:27], v[16:17], v[16:17]
	s_nop 0
	v_pk_mov_b32 v[28:29], v[26:27], v[24:25] op_sel:[1,0]
	v_mov_b32_e32 v27, v25
	v_pk_add_f32 v[24:25], v[28:29], v[26:27]
	s_waitcnt lgkmcnt(0)
	v_pk_mul_f32 v[26:27], v[22:23], v[22:23]
	v_pk_mul_f32 v[28:29], v[20:21], v[20:21]
	v_mov_b32_e32 v30, v26
	v_mov_b32_e32 v31, v28
	v_mov_b32_e32 v28, v27
	v_pk_add_f32 v[26:27], v[30:31], v[28:29]
	v_add_f32_e32 v3, v24, v25
	v_add_f32_e32 v3, v3, v27
	v_add_f32_e32 v3, v26, v3
	s_nop 1
	v_add_f32_dpp v3, v3, v3 quad_perm:[1,0,3,2] row_mask:0xf bank_mask:0xf bound_ctrl:1
	s_nop 1
	v_add_f32_dpp v3, v3, v3 quad_perm:[2,3,0,1] row_mask:0xf bank_mask:0xf bound_ctrl:1
	s_nop 1
	v_add_f32_dpp v3, v3, v3 row_half_mirror row_mask:0xf bank_mask:0xf bound_ctrl:1
	v_fmamk_f32 v3, v3, 0x3c800000, v218
	v_cmp_gt_f32_e32 vcc, s66, v3
	v_mul_f32_e32 v5, 0x4b800000, v3
	s_nop 0
	v_cndmask_b32_e32 v3, v3, v5, vcc
	v_rsq_f32_e32 v3, v3
	s_nop 0
	v_mul_f32_e32 v5, 0x45800000, v3
	v_cndmask_b32_e32 v3, v3, v5, vcc
	v_mul_f32_e32 v13, v20, v3
	v_or_b32_e32 v20, s60, v1
	v_mul_f32_e32 v15, v21, v3
	v_ashrrev_i32_e32 v21, 31, v20
	v_lshlrev_b64 v[20:21], 11, v[20:21]
	v_mul_f32_e32 v5, v16, v3
	v_lshl_add_u64 v[20:21], s[20:21], 0, v[20:21]
	v_mul_f32_e32 v5, v0, v5
	v_mul_f32_e32 v7, v17, v3
	v_mul_f32_e32 v16, v22, v3
	v_lshl_add_u64 v[20:21], v[20:21], 0, s[72:73]
	v_mul_f32_e32 v7, v2, v7
	v_mul_f32_e32 v9, v18, v3
	v_mul_f32_e32 v11, v19, v3
	v_mul_f32_e32 v19, v12, v16
	v_mul_f32_e32 v3, v23, v3
	v_cvt_pk_bf16_f32 v16, v5, v7
	v_lshl_add_u64 v[20:21], v[20:21], 0, v[216:217]
	v_or_b32_e32 v5, 24, v32
	v_mul_f32_e32 v9, v4, v9
	v_mul_f32_e32 v11, v6, v11
	v_mul_f32_e32 v13, v8, v13
	v_mul_f32_e32 v15, v10, v15
	v_mul_f32_e32 v3, v14, v3
	v_cvt_pk_bf16_f32 v17, v9, v11
	v_cvt_pk_bf16_f32 v18, v13, v15
	v_cvt_pk_bf16_f32 v19, v19, v3
	global_store_dwordx4 v[20:21], v[16:19], off offset:512
	v_lshl_add_u32 v1, v5, 8, v33
	ds_read_b128 v[16:19], v1
	ds_read_b128 v[20:23], v1 offset:16
	s_waitcnt lgkmcnt(1)
	v_pk_mul_f32 v[24:25], v[18:19], v[18:19]
	v_pk_mul_f32 v[26:27], v[16:17], v[16:17]
	s_nop 0
	v_pk_mov_b32 v[28:29], v[26:27], v[24:25] op_sel:[1,0]
	v_mov_b32_e32 v27, v25
	v_pk_add_f32 v[24:25], v[28:29], v[26:27]
	s_waitcnt lgkmcnt(0)
	v_pk_mul_f32 v[26:27], v[22:23], v[22:23]
	v_pk_mul_f32 v[28:29], v[20:21], v[20:21]
	v_mov_b32_e32 v30, v26
	v_mov_b32_e32 v31, v28
	v_mov_b32_e32 v28, v27
	v_pk_add_f32 v[26:27], v[30:31], v[28:29]
	v_add_f32_e32 v1, v24, v25
	v_add_f32_e32 v1, v1, v27
	v_add_f32_e32 v1, v26, v1
	s_nop 1
	v_add_f32_dpp v1, v1, v1 quad_perm:[1,0,3,2] row_mask:0xf bank_mask:0xf bound_ctrl:1
	s_nop 1
	v_add_f32_dpp v1, v1, v1 quad_perm:[2,3,0,1] row_mask:0xf bank_mask:0xf bound_ctrl:1
	s_nop 1
	v_add_f32_dpp v1, v1, v1 row_half_mirror row_mask:0xf bank_mask:0xf bound_ctrl:1
	v_fmamk_f32 v1, v1, 0x3c800000, v218
	v_cmp_gt_f32_e32 vcc, s66, v1
	v_mul_f32_e32 v3, 0x4b800000, v1
	s_nop 0
	v_cndmask_b32_e32 v1, v1, v3, vcc
	v_rsq_f32_e32 v1, v1
	s_nop 0
	v_mul_f32_e32 v3, 0x45800000, v1
	v_cndmask_b32_e32 v1, v1, v3, vcc
	v_mul_f32_e32 v3, v16, v1
	v_mul_f32_e32 v0, v0, v3
	v_mul_f32_e32 v3, v17, v1
	v_mul_f32_e32 v2, v2, v3
	v_mul_f32_e32 v3, v18, v1
	v_mul_f32_e32 v3, v4, v3
	v_mul_f32_e32 v4, v19, v1
	v_mul_f32_e32 v4, v6, v4
	v_mul_f32_e32 v6, v20, v1
	v_mul_f32_e32 v6, v8, v6
	v_mul_f32_e32 v7, v21, v1
	v_mul_f32_e32 v8, v22, v1
	v_mul_f32_e32 v1, v23, v1
	v_mul_f32_e32 v9, v14, v1
	v_cvt_pk_bf16_f32 v0, v0, v2
	v_cvt_pk_bf16_f32 v1, v3, v4
	v_or_b32_e32 v4, s60, v5
	v_ashrrev_i32_e32 v5, 31, v4
	v_lshlrev_b64 v[4:5], 11, v[4:5]
	v_lshl_add_u64 v[4:5], s[20:21], 0, v[4:5]
	v_lshl_add_u64 v[4:5], v[4:5], 0, s[72:73]
	v_lshl_add_u64 v[4:5], v[4:5], 0, v[216:217]
	v_mul_f32_e32 v7, v10, v7
	v_mul_f32_e32 v8, v12, v8
	v_cvt_pk_bf16_f32 v2, v6, v7
	v_cvt_pk_bf16_f32 v3, v8, v9
	global_store_dwordx4 v[4:5], v[0:3], off offset:512
	s_branch .Lat_afterA
